# adaLN: silu(c) staging loads issued together (was one load per wait)
# baseline (speedup 1.0000x reference)
; __device__ __forceinline__ void phase0(const Params& p, LAS unsigned char* lds, int wv) {
;     ...
;         for (int i = tid; i < 16 * 1024; i += 512) { const float v = p.c[i]; sc[i] = v / (1.f + __expf(-v)); }
.LBB0_36:
	s_mov_b64 s[12:13], 0x1000
	global_load_dword v16, v[4:5], off
	global_load_dword v17, v[4:5], off offset:2048
	v_lshl_add_u64 v[4:5], v[4:5], 0, s[12:13]
	global_load_dword v18, v[4:5], off
	global_load_dword v19, v[4:5], off offset:2048
	v_lshl_add_u64 v[4:5], v[4:5], 0, s[12:13]
	global_load_dword v20, v[4:5], off
	global_load_dword v21, v[4:5], off offset:2048
	v_lshl_add_u64 v[4:5], v[4:5], 0, s[12:13]
	global_load_dword v22, v[4:5], off
	global_load_dword v23, v[4:5], off offset:2048
	v_lshl_add_u64 v[4:5], v[4:5], 0, s[12:13]
	global_load_dword v24, v[4:5], off
	global_load_dword v25, v[4:5], off offset:2048
	v_lshl_add_u64 v[4:5], v[4:5], 0, s[12:13]
	global_load_dword v26, v[4:5], off
	global_load_dword v27, v[4:5], off offset:2048
	v_lshl_add_u64 v[4:5], v[4:5], 0, s[12:13]
	global_load_dword v28, v[4:5], off
	global_load_dword v29, v[4:5], off offset:2048
	v_lshl_add_u64 v[4:5], v[4:5], 0, s[12:13]
	global_load_dword v30, v[4:5], off
	global_load_dword v31, v[4:5], off offset:2048
	v_lshl_add_u64 v[4:5], v[4:5], 0, s[12:13]
	global_load_dword v32, v[4:5], off
	global_load_dword v33, v[4:5], off offset:2048
	v_lshl_add_u64 v[4:5], v[4:5], 0, s[12:13]
	global_load_dword v34, v[4:5], off
	global_load_dword v35, v[4:5], off offset:2048
	v_lshl_add_u64 v[4:5], v[4:5], 0, s[12:13]
	global_load_dword v36, v[4:5], off
	global_load_dword v37, v[4:5], off offset:2048
	v_lshl_add_u64 v[4:5], v[4:5], 0, s[12:13]
	global_load_dword v38, v[4:5], off
	global_load_dword v39, v[4:5], off offset:2048
	v_lshl_add_u64 v[4:5], v[4:5], 0, s[12:13]
	global_load_dword v40, v[4:5], off
	global_load_dword v41, v[4:5], off offset:2048
	v_lshl_add_u64 v[4:5], v[4:5], 0, s[12:13]
	global_load_dword v42, v[4:5], off
	global_load_dword v43, v[4:5], off offset:2048
	v_lshl_add_u64 v[4:5], v[4:5], 0, s[12:13]
	global_load_dword v44, v[4:5], off
	global_load_dword v45, v[4:5], off offset:2048
	v_lshl_add_u64 v[4:5], v[4:5], 0, s[12:13]
	global_load_dword v46, v[4:5], off
	global_load_dword v47, v[4:5], off offset:2048
	s_waitcnt vmcnt(31)
	v_mul_f32_e32 v8, 0xbfb8aa3b, v16
	v_exp_f32_e32 v8, v8
	s_nop 0
	v_add_f32_e32 v8, 1.0, v8
	v_div_scale_f32 v9, s[16:17], v8, v8, v16
	v_rcp_f32_e32 v10, v9
	v_div_scale_f32 v11, vcc, v16, v8, v16
	v_fma_f32 v12, -v9, v10, 1.0
	v_fmac_f32_e32 v10, v12, v10
	v_mul_f32_e32 v12, v11, v10
	v_fma_f32 v13, -v9, v12, v11
	v_fmac_f32_e32 v12, v13, v10
	v_fma_f32 v9, -v9, v12, v11
	v_div_fmas_f32 v9, v9, v10, v12
	v_div_fixup_f32 v3, v9, v8, v16
	ds_write_b32 v7, v3
	s_waitcnt vmcnt(30)
	v_mul_f32_e32 v8, 0xbfb8aa3b, v17
	v_exp_f32_e32 v8, v8
	s_nop 0
	v_add_f32_e32 v8, 1.0, v8
	v_div_scale_f32 v9, s[16:17], v8, v8, v17
	v_rcp_f32_e32 v10, v9
	v_div_scale_f32 v11, vcc, v17, v8, v17
	v_fma_f32 v12, -v9, v10, 1.0
	v_fmac_f32_e32 v10, v12, v10
	v_mul_f32_e32 v12, v11, v10
	v_fma_f32 v13, -v9, v12, v11
	v_fmac_f32_e32 v12, v13, v10
	v_fma_f32 v9, -v9, v12, v11
	v_div_fmas_f32 v9, v9, v10, v12
	v_div_fixup_f32 v3, v9, v8, v17
	ds_write_b32 v7, v3 offset:2048
	s_waitcnt vmcnt(29)
	v_mul_f32_e32 v8, 0xbfb8aa3b, v18
	v_exp_f32_e32 v8, v8
	s_nop 0
	v_add_f32_e32 v8, 1.0, v8
	v_div_scale_f32 v9, s[16:17], v8, v8, v18
	v_rcp_f32_e32 v10, v9
	v_div_scale_f32 v11, vcc, v18, v8, v18
	v_fma_f32 v12, -v9, v10, 1.0
	v_fmac_f32_e32 v10, v12, v10
	v_mul_f32_e32 v12, v11, v10
	v_fma_f32 v13, -v9, v12, v11
	v_fmac_f32_e32 v12, v13, v10
	v_fma_f32 v9, -v9, v12, v11
	v_div_fmas_f32 v9, v9, v10, v12
	v_div_fixup_f32 v3, v9, v8, v18
	ds_write_b32 v7, v3 offset:4096
	s_waitcnt vmcnt(28)
	v_mul_f32_e32 v8, 0xbfb8aa3b, v19
	v_exp_f32_e32 v8, v8
	s_nop 0
	v_add_f32_e32 v8, 1.0, v8
	v_div_scale_f32 v9, s[16:17], v8, v8, v19
	v_rcp_f32_e32 v10, v9
	v_div_scale_f32 v11, vcc, v19, v8, v19
	v_fma_f32 v12, -v9, v10, 1.0
	v_fmac_f32_e32 v10, v12, v10
	v_mul_f32_e32 v12, v11, v10
	v_fma_f32 v13, -v9, v12, v11
	v_fmac_f32_e32 v12, v13, v10
	v_fma_f32 v9, -v9, v12, v11
	v_div_fmas_f32 v9, v9, v10, v12
	v_div_fixup_f32 v3, v9, v8, v19
	ds_write_b32 v7, v3 offset:6144
	s_waitcnt vmcnt(27)
	v_mul_f32_e32 v8, 0xbfb8aa3b, v20
	v_exp_f32_e32 v8, v8
	s_nop 0
	v_add_f32_e32 v8, 1.0, v8
	v_div_scale_f32 v9, s[16:17], v8, v8, v20
	v_rcp_f32_e32 v10, v9
	v_div_scale_f32 v11, vcc, v20, v8, v20
	v_fma_f32 v12, -v9, v10, 1.0
	v_fmac_f32_e32 v10, v12, v10
	v_mul_f32_e32 v12, v11, v10
	v_fma_f32 v13, -v9, v12, v11
	v_fmac_f32_e32 v12, v13, v10
	v_fma_f32 v9, -v9, v12, v11
	v_div_fmas_f32 v9, v9, v10, v12
	v_div_fixup_f32 v3, v9, v8, v20
	ds_write_b32 v7, v3 offset:8192
	s_waitcnt vmcnt(26)
	v_mul_f32_e32 v8, 0xbfb8aa3b, v21
	v_exp_f32_e32 v8, v8
	s_nop 0
	v_add_f32_e32 v8, 1.0, v8
	v_div_scale_f32 v9, s[16:17], v8, v8, v21
	v_rcp_f32_e32 v10, v9
	v_div_scale_f32 v11, vcc, v21, v8, v21
	v_fma_f32 v12, -v9, v10, 1.0
	v_fmac_f32_e32 v10, v12, v10
	v_mul_f32_e32 v12, v11, v10
	v_fma_f32 v13, -v9, v12, v11
	v_fmac_f32_e32 v12, v13, v10
	v_fma_f32 v9, -v9, v12, v11
	v_div_fmas_f32 v9, v9, v10, v12
	v_div_fixup_f32 v3, v9, v8, v21
	ds_write_b32 v7, v3 offset:10240
	s_waitcnt vmcnt(25)
	v_mul_f32_e32 v8, 0xbfb8aa3b, v22
	v_exp_f32_e32 v8, v8
	s_nop 0
	v_add_f32_e32 v8, 1.0, v8
	v_div_scale_f32 v9, s[16:17], v8, v8, v22
	v_rcp_f32_e32 v10, v9
	v_div_scale_f32 v11, vcc, v22, v8, v22
	v_fma_f32 v12, -v9, v10, 1.0
	v_fmac_f32_e32 v10, v12, v10
	v_mul_f32_e32 v12, v11, v10
	v_fma_f32 v13, -v9, v12, v11
	v_fmac_f32_e32 v12, v13, v10
	v_fma_f32 v9, -v9, v12, v11
	v_div_fmas_f32 v9, v9, v10, v12
	v_div_fixup_f32 v3, v9, v8, v22
	ds_write_b32 v7, v3 offset:12288
	s_waitcnt vmcnt(24)
; __device__ __forceinline__ void phase0(const Params& p, LAS unsigned char* lds, int wv) {
;     ...
;         for (int i = tid; i < 16 * 1024; i += 512) { const float v = p.c[i]; sc[i] = v / (1.f + __expf(-v)); }
	v_mul_f32_e32 v8, 0xbfb8aa3b, v23
	v_exp_f32_e32 v8, v8
	s_nop 0
	v_add_f32_e32 v8, 1.0, v8
	v_div_scale_f32 v9, s[16:17], v8, v8, v23
	v_rcp_f32_e32 v10, v9
	v_div_scale_f32 v11, vcc, v23, v8, v23
	v_fma_f32 v12, -v9, v10, 1.0
	v_fmac_f32_e32 v10, v12, v10
	v_mul_f32_e32 v12, v11, v10
	v_fma_f32 v13, -v9, v12, v11
	v_fmac_f32_e32 v12, v13, v10
	v_fma_f32 v9, -v9, v12, v11
	v_div_fmas_f32 v9, v9, v10, v12
	v_div_fixup_f32 v3, v9, v8, v23
	ds_write_b32 v7, v3 offset:14336
	s_waitcnt vmcnt(23)
	v_mul_f32_e32 v8, 0xbfb8aa3b, v24
	v_exp_f32_e32 v8, v8
	s_nop 0
	v_add_f32_e32 v8, 1.0, v8
	v_div_scale_f32 v9, s[16:17], v8, v8, v24
	v_rcp_f32_e32 v10, v9
	v_div_scale_f32 v11, vcc, v24, v8, v24
	v_fma_f32 v12, -v9, v10, 1.0
	v_fmac_f32_e32 v10, v12, v10
	v_mul_f32_e32 v12, v11, v10
	v_fma_f32 v13, -v9, v12, v11
	v_fmac_f32_e32 v12, v13, v10
	v_fma_f32 v9, -v9, v12, v11
	v_div_fmas_f32 v9, v9, v10, v12
	v_div_fixup_f32 v3, v9, v8, v24
	ds_write_b32 v7, v3 offset:16384
	s_waitcnt vmcnt(22)
	v_mul_f32_e32 v8, 0xbfb8aa3b, v25
	v_exp_f32_e32 v8, v8
	s_nop 0
	v_add_f32_e32 v8, 1.0, v8
	v_div_scale_f32 v9, s[16:17], v8, v8, v25
	v_rcp_f32_e32 v10, v9
	v_div_scale_f32 v11, vcc, v25, v8, v25
	v_fma_f32 v12, -v9, v10, 1.0
	v_fmac_f32_e32 v10, v12, v10
	v_mul_f32_e32 v12, v11, v10
	v_fma_f32 v13, -v9, v12, v11
	v_fmac_f32_e32 v12, v13, v10
	v_fma_f32 v9, -v9, v12, v11
	v_div_fmas_f32 v9, v9, v10, v12
	v_div_fixup_f32 v3, v9, v8, v25
	ds_write_b32 v7, v3 offset:18432
	s_waitcnt vmcnt(21)
	v_mul_f32_e32 v8, 0xbfb8aa3b, v26
	v_exp_f32_e32 v8, v8
	s_nop 0
	v_add_f32_e32 v8, 1.0, v8
	v_div_scale_f32 v9, s[16:17], v8, v8, v26
	v_rcp_f32_e32 v10, v9
	v_div_scale_f32 v11, vcc, v26, v8, v26
	v_fma_f32 v12, -v9, v10, 1.0
	v_fmac_f32_e32 v10, v12, v10
	v_mul_f32_e32 v12, v11, v10
	v_fma_f32 v13, -v9, v12, v11
	v_fmac_f32_e32 v12, v13, v10
	v_fma_f32 v9, -v9, v12, v11
	v_div_fmas_f32 v9, v9, v10, v12
	v_div_fixup_f32 v3, v9, v8, v26
	ds_write_b32 v7, v3 offset:20480
	s_waitcnt vmcnt(20)
	v_mul_f32_e32 v8, 0xbfb8aa3b, v27
	v_exp_f32_e32 v8, v8
	s_nop 0
	v_add_f32_e32 v8, 1.0, v8
	v_div_scale_f32 v9, s[16:17], v8, v8, v27
	v_rcp_f32_e32 v10, v9
	v_div_scale_f32 v11, vcc, v27, v8, v27
	v_fma_f32 v12, -v9, v10, 1.0
	v_fmac_f32_e32 v10, v12, v10
	v_mul_f32_e32 v12, v11, v10
	v_fma_f32 v13, -v9, v12, v11
	v_fmac_f32_e32 v12, v13, v10
	v_fma_f32 v9, -v9, v12, v11
	v_div_fmas_f32 v9, v9, v10, v12
	v_div_fixup_f32 v3, v9, v8, v27
	ds_write_b32 v7, v3 offset:22528
	s_waitcnt vmcnt(19)
	v_mul_f32_e32 v8, 0xbfb8aa3b, v28
	v_exp_f32_e32 v8, v8
	s_nop 0
	v_add_f32_e32 v8, 1.0, v8
	v_div_scale_f32 v9, s[16:17], v8, v8, v28
	v_rcp_f32_e32 v10, v9
	v_div_scale_f32 v11, vcc, v28, v8, v28
	v_fma_f32 v12, -v9, v10, 1.0
	v_fmac_f32_e32 v10, v12, v10
	v_mul_f32_e32 v12, v11, v10
	v_fma_f32 v13, -v9, v12, v11
	v_fmac_f32_e32 v12, v13, v10
	v_fma_f32 v9, -v9, v12, v11
	v_div_fmas_f32 v9, v9, v10, v12
	v_div_fixup_f32 v3, v9, v8, v28
	ds_write_b32 v7, v3 offset:24576
	s_waitcnt vmcnt(18)
	v_mul_f32_e32 v8, 0xbfb8aa3b, v29
	v_exp_f32_e32 v8, v8
	s_nop 0
	v_add_f32_e32 v8, 1.0, v8
	v_div_scale_f32 v9, s[16:17], v8, v8, v29
	v_rcp_f32_e32 v10, v9
	v_div_scale_f32 v11, vcc, v29, v8, v29
	v_fma_f32 v12, -v9, v10, 1.0
	v_fmac_f32_e32 v10, v12, v10
	v_mul_f32_e32 v12, v11, v10
	v_fma_f32 v13, -v9, v12, v11
	v_fmac_f32_e32 v12, v13, v10
	v_fma_f32 v9, -v9, v12, v11
	v_div_fmas_f32 v9, v9, v10, v12
	v_div_fixup_f32 v3, v9, v8, v29
	ds_write_b32 v7, v3 offset:26624
	s_waitcnt vmcnt(17)
	v_mul_f32_e32 v8, 0xbfb8aa3b, v30
	v_exp_f32_e32 v8, v8
	s_nop 0
	v_add_f32_e32 v8, 1.0, v8
	v_div_scale_f32 v9, s[16:17], v8, v8, v30
	v_rcp_f32_e32 v10, v9
	v_div_scale_f32 v11, vcc, v30, v8, v30
	v_fma_f32 v12, -v9, v10, 1.0
	v_fmac_f32_e32 v10, v12, v10
	v_mul_f32_e32 v12, v11, v10
	v_fma_f32 v13, -v9, v12, v11
	v_fmac_f32_e32 v12, v13, v10
	v_fma_f32 v9, -v9, v12, v11
	v_div_fmas_f32 v9, v9, v10, v12
	v_div_fixup_f32 v3, v9, v8, v30
	ds_write_b32 v7, v3 offset:28672
	s_waitcnt vmcnt(16)
	v_mul_f32_e32 v8, 0xbfb8aa3b, v31
	v_exp_f32_e32 v8, v8
	s_nop 0
	v_add_f32_e32 v8, 1.0, v8
	v_div_scale_f32 v9, s[16:17], v8, v8, v31
	v_rcp_f32_e32 v10, v9
	v_div_scale_f32 v11, vcc, v31, v8, v31
	v_fma_f32 v12, -v9, v10, 1.0
	v_fmac_f32_e32 v10, v12, v10
	v_mul_f32_e32 v12, v11, v10
	v_fma_f32 v13, -v9, v12, v11
	v_fmac_f32_e32 v12, v13, v10
	v_fma_f32 v9, -v9, v12, v11
	v_div_fmas_f32 v9, v9, v10, v12
	v_div_fixup_f32 v3, v9, v8, v31
	ds_write_b32 v7, v3 offset:30720
	s_waitcnt vmcnt(15)
	v_mul_f32_e32 v8, 0xbfb8aa3b, v32
	v_exp_f32_e32 v8, v8
	s_nop 0
	v_add_f32_e32 v8, 1.0, v8
	v_div_scale_f32 v9, s[16:17], v8, v8, v32
	v_rcp_f32_e32 v10, v9
	v_div_scale_f32 v11, vcc, v32, v8, v32
	v_fma_f32 v12, -v9, v10, 1.0
	v_fmac_f32_e32 v10, v12, v10
	v_mul_f32_e32 v12, v11, v10
	v_fma_f32 v13, -v9, v12, v11
	v_fmac_f32_e32 v12, v13, v10
	v_fma_f32 v9, -v9, v12, v11
	v_div_fmas_f32 v9, v9, v10, v12
	v_div_fixup_f32 v3, v9, v8, v32
	ds_write_b32 v7, v3 offset:32768
	s_waitcnt vmcnt(14)
	v_mul_f32_e32 v8, 0xbfb8aa3b, v33
	v_exp_f32_e32 v8, v8
	s_nop 0
	v_add_f32_e32 v8, 1.0, v8
	v_div_scale_f32 v9, s[16:17], v8, v8, v33
	v_rcp_f32_e32 v10, v9
	v_div_scale_f32 v11, vcc, v33, v8, v33
	v_fma_f32 v12, -v9, v10, 1.0
	v_fmac_f32_e32 v10, v12, v10
	v_mul_f32_e32 v12, v11, v10
	v_fma_f32 v13, -v9, v12, v11
	v_fmac_f32_e32 v12, v13, v10
	v_fma_f32 v9, -v9, v12, v11
	v_div_fmas_f32 v9, v9, v10, v12
	v_div_fixup_f32 v3, v9, v8, v33
	ds_write_b32 v7, v3 offset:34816
	s_waitcnt vmcnt(13)
; __device__ __forceinline__ void phase0(const Params& p, LAS unsigned char* lds, int wv) {
;     ...
;         for (int i = tid; i < 16 * 1024; i += 512) { const float v = p.c[i]; sc[i] = v / (1.f + __expf(-v)); }
	v_mul_f32_e32 v8, 0xbfb8aa3b, v34
	v_exp_f32_e32 v8, v8
	s_nop 0
	v_add_f32_e32 v8, 1.0, v8
	v_div_scale_f32 v9, s[16:17], v8, v8, v34
	v_rcp_f32_e32 v10, v9
	v_div_scale_f32 v11, vcc, v34, v8, v34
	v_fma_f32 v12, -v9, v10, 1.0
	v_fmac_f32_e32 v10, v12, v10
	v_mul_f32_e32 v12, v11, v10
	v_fma_f32 v13, -v9, v12, v11
	v_fmac_f32_e32 v12, v13, v10
	v_fma_f32 v9, -v9, v12, v11
	v_div_fmas_f32 v9, v9, v10, v12
	v_div_fixup_f32 v3, v9, v8, v34
	ds_write_b32 v7, v3 offset:36864
	s_waitcnt vmcnt(12)
	v_mul_f32_e32 v8, 0xbfb8aa3b, v35
	v_exp_f32_e32 v8, v8
	s_nop 0
	v_add_f32_e32 v8, 1.0, v8
	v_div_scale_f32 v9, s[16:17], v8, v8, v35
	v_rcp_f32_e32 v10, v9
	v_div_scale_f32 v11, vcc, v35, v8, v35
	v_fma_f32 v12, -v9, v10, 1.0
	v_fmac_f32_e32 v10, v12, v10
	v_mul_f32_e32 v12, v11, v10
	v_fma_f32 v13, -v9, v12, v11
	v_fmac_f32_e32 v12, v13, v10
	v_fma_f32 v9, -v9, v12, v11
	v_div_fmas_f32 v9, v9, v10, v12
	v_div_fixup_f32 v3, v9, v8, v35
	ds_write_b32 v7, v3 offset:38912
	s_waitcnt vmcnt(11)
	v_mul_f32_e32 v8, 0xbfb8aa3b, v36
	v_exp_f32_e32 v8, v8
	s_nop 0
	v_add_f32_e32 v8, 1.0, v8
	v_div_scale_f32 v9, s[16:17], v8, v8, v36
	v_rcp_f32_e32 v10, v9
	v_div_scale_f32 v11, vcc, v36, v8, v36
	v_fma_f32 v12, -v9, v10, 1.0
	v_fmac_f32_e32 v10, v12, v10
	v_mul_f32_e32 v12, v11, v10
	v_fma_f32 v13, -v9, v12, v11
	v_fmac_f32_e32 v12, v13, v10
	v_fma_f32 v9, -v9, v12, v11
	v_div_fmas_f32 v9, v9, v10, v12
	v_div_fixup_f32 v3, v9, v8, v36
	ds_write_b32 v7, v3 offset:40960
	s_waitcnt vmcnt(10)
	v_mul_f32_e32 v8, 0xbfb8aa3b, v37
	v_exp_f32_e32 v8, v8
	s_nop 0
	v_add_f32_e32 v8, 1.0, v8
	v_div_scale_f32 v9, s[16:17], v8, v8, v37
	v_rcp_f32_e32 v10, v9
	v_div_scale_f32 v11, vcc, v37, v8, v37
	v_fma_f32 v12, -v9, v10, 1.0
	v_fmac_f32_e32 v10, v12, v10
	v_mul_f32_e32 v12, v11, v10
	v_fma_f32 v13, -v9, v12, v11
	v_fmac_f32_e32 v12, v13, v10
	v_fma_f32 v9, -v9, v12, v11
	v_div_fmas_f32 v9, v9, v10, v12
	v_div_fixup_f32 v3, v9, v8, v37
	ds_write_b32 v7, v3 offset:43008
	s_waitcnt vmcnt(9)
	v_mul_f32_e32 v8, 0xbfb8aa3b, v38
	v_exp_f32_e32 v8, v8
	s_nop 0
	v_add_f32_e32 v8, 1.0, v8
	v_div_scale_f32 v9, s[16:17], v8, v8, v38
	v_rcp_f32_e32 v10, v9
	v_div_scale_f32 v11, vcc, v38, v8, v38
	v_fma_f32 v12, -v9, v10, 1.0
	v_fmac_f32_e32 v10, v12, v10
	v_mul_f32_e32 v12, v11, v10
	v_fma_f32 v13, -v9, v12, v11
	v_fmac_f32_e32 v12, v13, v10
	v_fma_f32 v9, -v9, v12, v11
	v_div_fmas_f32 v9, v9, v10, v12
	v_div_fixup_f32 v3, v9, v8, v38
	ds_write_b32 v7, v3 offset:45056
	s_waitcnt vmcnt(8)
	v_mul_f32_e32 v8, 0xbfb8aa3b, v39
	v_exp_f32_e32 v8, v8
	s_nop 0
	v_add_f32_e32 v8, 1.0, v8
	v_div_scale_f32 v9, s[16:17], v8, v8, v39
	v_rcp_f32_e32 v10, v9
	v_div_scale_f32 v11, vcc, v39, v8, v39
	v_fma_f32 v12, -v9, v10, 1.0
	v_fmac_f32_e32 v10, v12, v10
	v_mul_f32_e32 v12, v11, v10
	v_fma_f32 v13, -v9, v12, v11
	v_fmac_f32_e32 v12, v13, v10
	v_fma_f32 v9, -v9, v12, v11
	v_div_fmas_f32 v9, v9, v10, v12
	v_div_fixup_f32 v3, v9, v8, v39
	ds_write_b32 v7, v3 offset:47104
	s_waitcnt vmcnt(7)
	v_mul_f32_e32 v8, 0xbfb8aa3b, v40
	v_exp_f32_e32 v8, v8
	s_nop 0
	v_add_f32_e32 v8, 1.0, v8
	v_div_scale_f32 v9, s[16:17], v8, v8, v40
	v_rcp_f32_e32 v10, v9
	v_div_scale_f32 v11, vcc, v40, v8, v40
	v_fma_f32 v12, -v9, v10, 1.0
	v_fmac_f32_e32 v10, v12, v10
	v_mul_f32_e32 v12, v11, v10
	v_fma_f32 v13, -v9, v12, v11
	v_fmac_f32_e32 v12, v13, v10
	v_fma_f32 v9, -v9, v12, v11
	v_div_fmas_f32 v9, v9, v10, v12
	v_div_fixup_f32 v3, v9, v8, v40
	ds_write_b32 v7, v3 offset:49152
	s_waitcnt vmcnt(6)
	v_mul_f32_e32 v8, 0xbfb8aa3b, v41
	v_exp_f32_e32 v8, v8
	s_nop 0
	v_add_f32_e32 v8, 1.0, v8
	v_div_scale_f32 v9, s[16:17], v8, v8, v41
	v_rcp_f32_e32 v10, v9
	v_div_scale_f32 v11, vcc, v41, v8, v41
	v_fma_f32 v12, -v9, v10, 1.0
	v_fmac_f32_e32 v10, v12, v10
	v_mul_f32_e32 v12, v11, v10
	v_fma_f32 v13, -v9, v12, v11
	v_fmac_f32_e32 v12, v13, v10
	v_fma_f32 v9, -v9, v12, v11
	v_div_fmas_f32 v9, v9, v10, v12
	v_div_fixup_f32 v3, v9, v8, v41
	ds_write_b32 v7, v3 offset:51200
	s_waitcnt vmcnt(5)
	v_mul_f32_e32 v8, 0xbfb8aa3b, v42
	v_exp_f32_e32 v8, v8
	s_nop 0
	v_add_f32_e32 v8, 1.0, v8
	v_div_scale_f32 v9, s[16:17], v8, v8, v42
	v_rcp_f32_e32 v10, v9
	v_div_scale_f32 v11, vcc, v42, v8, v42
	v_fma_f32 v12, -v9, v10, 1.0
	v_fmac_f32_e32 v10, v12, v10
	v_mul_f32_e32 v12, v11, v10
	v_fma_f32 v13, -v9, v12, v11
	v_fmac_f32_e32 v12, v13, v10
	v_fma_f32 v9, -v9, v12, v11
	v_div_fmas_f32 v9, v9, v10, v12
	v_div_fixup_f32 v3, v9, v8, v42
	ds_write_b32 v7, v3 offset:53248
	s_waitcnt vmcnt(4)
	v_mul_f32_e32 v8, 0xbfb8aa3b, v43
	v_exp_f32_e32 v8, v8
	s_nop 0
	v_add_f32_e32 v8, 1.0, v8
	v_div_scale_f32 v9, s[16:17], v8, v8, v43
	v_rcp_f32_e32 v10, v9
	v_div_scale_f32 v11, vcc, v43, v8, v43
	v_fma_f32 v12, -v9, v10, 1.0
	v_fmac_f32_e32 v10, v12, v10
	v_mul_f32_e32 v12, v11, v10
	v_fma_f32 v13, -v9, v12, v11
	v_fmac_f32_e32 v12, v13, v10
	v_fma_f32 v9, -v9, v12, v11
	v_div_fmas_f32 v9, v9, v10, v12
	v_div_fixup_f32 v3, v9, v8, v43
	ds_write_b32 v7, v3 offset:55296
	s_waitcnt vmcnt(3)
	v_mul_f32_e32 v8, 0xbfb8aa3b, v44
	v_exp_f32_e32 v8, v8
	s_nop 0
	v_add_f32_e32 v8, 1.0, v8
	v_div_scale_f32 v9, s[16:17], v8, v8, v44
	v_rcp_f32_e32 v10, v9
	v_div_scale_f32 v11, vcc, v44, v8, v44
	v_fma_f32 v12, -v9, v10, 1.0
	v_fmac_f32_e32 v10, v12, v10
	v_mul_f32_e32 v12, v11, v10
	v_fma_f32 v13, -v9, v12, v11
	v_fmac_f32_e32 v12, v13, v10
	v_fma_f32 v9, -v9, v12, v11
	v_div_fmas_f32 v9, v9, v10, v12
	v_div_fixup_f32 v3, v9, v8, v44
	ds_write_b32 v7, v3 offset:57344
	s_waitcnt vmcnt(2)
	v_mul_f32_e32 v8, 0xbfb8aa3b, v45
	v_exp_f32_e32 v8, v8
	s_nop 0
	v_add_f32_e32 v8, 1.0, v8
	v_div_scale_f32 v9, s[16:17], v8, v8, v45
	v_rcp_f32_e32 v10, v9
	v_div_scale_f32 v11, vcc, v45, v8, v45
	v_fma_f32 v12, -v9, v10, 1.0
	v_fmac_f32_e32 v10, v12, v10
	v_mul_f32_e32 v12, v11, v10
	v_fma_f32 v13, -v9, v12, v11
	v_fmac_f32_e32 v12, v13, v10
	v_fma_f32 v9, -v9, v12, v11
	v_div_fmas_f32 v9, v9, v10, v12
	v_div_fixup_f32 v3, v9, v8, v45
	ds_write_b32 v7, v3 offset:59392
	s_waitcnt vmcnt(1)
	v_mul_f32_e32 v8, 0xbfb8aa3b, v46
	v_exp_f32_e32 v8, v8
	s_nop 0
	v_add_f32_e32 v8, 1.0, v8
	v_div_scale_f32 v9, s[16:17], v8, v8, v46
	v_rcp_f32_e32 v10, v9
	v_div_scale_f32 v11, vcc, v46, v8, v46
	v_fma_f32 v12, -v9, v10, 1.0
	v_fmac_f32_e32 v10, v12, v10
	v_mul_f32_e32 v12, v11, v10
	v_fma_f32 v13, -v9, v12, v11
	v_fmac_f32_e32 v12, v13, v10
	v_fma_f32 v9, -v9, v12, v11
	v_div_fmas_f32 v9, v9, v10, v12
	v_div_fixup_f32 v3, v9, v8, v46
	ds_write_b32 v7, v3 offset:61440
	s_waitcnt vmcnt(0)
	v_mul_f32_e32 v8, 0xbfb8aa3b, v47
	v_exp_f32_e32 v8, v8
	s_nop 0
	v_add_f32_e32 v8, 1.0, v8
	v_div_scale_f32 v9, s[16:17], v8, v8, v47
	v_rcp_f32_e32 v10, v9
	v_div_scale_f32 v11, vcc, v47, v8, v47
	v_fma_f32 v12, -v9, v10, 1.0
	v_fmac_f32_e32 v10, v12, v10
	v_mul_f32_e32 v12, v11, v10
	v_fma_f32 v13, -v9, v12, v11
	v_fmac_f32_e32 v12, v13, v10
	v_fma_f32 v9, -v9, v12, v11
	v_div_fmas_f32 v9, v9, v10, v12
	v_div_fixup_f32 v3, v9, v8, v47
	ds_write_b32 v7, v3 offset:63488
